# attention: Q-fragment loads issued at the top of each head iteration, before the staging barrier
# baseline (speedup 1.0000x reference)
; __device__ __forceinline__ void sb_attn_wave(LAS unsigned char* lds, int Tlo, const bf16* __restrict__ u, const bf16* __restrict__ um, const bf16* __restrict__ vT, const bf16* __restrict__ vTm, ...
;     ...
;     AttnState st; st.o0 = (f32x16){}; st.o1 = (f32x16){}; st.carry = 1.f;
;     bool done = false;
;     int t = (P0 + 30) >> 6;
; __global__ void __launch_bounds__(NTHREADS, 2) trunk_fwd(Args a) {
;     ...
;                 int b = wv >> 3, h = it, P0 = NMETA + 256 * jb + 32 * rb, Tlo = Tl0;
;                 bf16* orow = WSP(bf16, WS_MIX) + ((size_t)b * SEQ + (P0 - NMETA) + (lane & 31)) * D + 512;
;                 if (it == 8) { b = 0; h = wave; P0 = 0; Tlo = 1; orow = (lane & 31) < NMETA ? WSP(bf16, WS_META + MB_MIXM) + (lane & 31) * D + 512 : nullptr; }
;                 asm volatile("" : "+s"(b), "+s"(h), "+s"(P0), "+s"(Tlo));
;                 __syncthreads();
;                 if (it < 8) attn_stage_store(lds, kx, vx, tid);
;                 __syncthreads();
;                 bf16x8 qf[4];
;                 { const bf16* qr = urow(WSP(const bf16, WS_U), WSP(const bf16, WS_META + MB_UM), b, P0 + (lane & 31)) + 1024 + h * 64 + 8 * (lane >> 5);
; #pragma unroll
;                   for (int d0 = 0; d0 < 4; ++d0) qf[d0] = *(const bf16x8*)(qr + 16 * d0); }
;                 attn_stage_load(kx, vx, WSP(const bf16, WS_U), WSP(const bf16, WS_META + MB_UM), WSP(const bf16, WS_VT), WSP(const bf16, WS_META + MB_VTM), wv >> 3, (it + 1 < 8) ? it + 1 : 7, Tl0, tid);
;                 sb_attn_wave(lds, Tlo, WSP(const bf16, WS_U), WSP(const bf16, WS_META + MB_UM), WSP(const bf16, WS_VT), WSP(const bf16, WS_META + MB_VTM), b, h, P0, qf, orow, lane);
.LBB0_272:
	v_add_u32_e32 v2, s53, v193
	v_cmp_lt_i32_e32 vcc, 15, v2
	s_and_saveexec_b64 s[46:47], vcc
	s_xor_b64 s[46:47], exec, s[46:47]
	s_ashr_i32 s41, s40, 31
	s_lshl_b64 s[48:49], s[40:41], 23
	v_add_u32_e32 v0, -16, v2
	s_add_u32 s48, s75, s48
	s_addc_u32 s49, s78, s49
	v_mov_b64_e32 v[2:3], v[0:1]
	s_or_saveexec_b64 s[46:47], s[46:47]
	v_mov_b64_e32 v[4:5], s[48:49]
	s_xor_b64 exec, exec, s[46:47]
	v_ashrrev_i32_e32 v3, 31, v2
	v_mov_b64_e32 v[4:5], s[22:23]
	s_or_b64 exec, exec, s[46:47]
	v_lshlrev_b64 v[2:3], 12, v[2:3]
	s_lshl_b32 s46, s54, 6
	s_add_i32 s54, s56, 1
	v_lshl_add_u64 v[2:3], v[4:5], 0, v[2:3]
	s_ashr_i32 s47, s46, 31
	s_lshl_b32 s41, s54, 6
	v_lshl_add_u64 v[2:3], s[46:47], 1, v[2:3]
	v_mov_b32_e32 v211, v1
	s_cmp_lt_u32 s56, 7
	v_lshl_add_u64 v[2:3], v[2:3], 0, v[210:211]
	s_cselect_b32 s70, s41, 0x1c0
	global_load_dwordx4 v[136:139], v[2:3], off offset:2048
	global_load_dwordx4 v[140:143], v[2:3], off offset:2080
	global_load_dwordx4 v[144:147], v[2:3], off offset:2112
	global_load_dwordx4 v[148:151], v[2:3], off offset:2144
	s_cmp_gt_u32 s56, 7
	s_barrier
	s_cbranch_scc1 .LBB0_274
	s_waitcnt vmcnt(16)
	ds_write_b128 v242, v[80:83]
	ds_write_b128 v173, v[84:87]
	s_waitcnt vmcnt(15)
	ds_write_b128 v242, v[88:91] offset:9216
	s_waitcnt vmcnt(13)
	ds_write_b128 v173, v[100:103] offset:9216
	ds_write_b128 v242, v[96:99] offset:18432
	s_waitcnt vmcnt(12)
	ds_write_b128 v173, v[92:95] offset:18432
	s_waitcnt vmcnt(11)
	ds_write_b128 v242, v[104:107] offset:27648
	s_waitcnt vmcnt(9)
	ds_write_b128 v173, v[116:119] offset:27648
	ds_write_b128 v242, v[112:115] offset:36864
	s_waitcnt vmcnt(8)
	ds_write_b128 v173, v[108:111] offset:36864
	s_waitcnt vmcnt(7)
	ds_write_b128 v242, v[120:123] offset:46080
	s_waitcnt vmcnt(5)
	ds_write_b128 v173, v[128:131] offset:46080
	ds_write_b128 v242, v[124:127] offset:55296
	s_waitcnt vmcnt(4)
	ds_write_b128 v173, v[132:135] offset:55296
.LBB0_274:
	s_waitcnt lgkmcnt(0)
	s_barrier
	v_add_u32_e32 v2, s70, v172
	v_ashrrev_i32_e32 v3, 31, v2
	v_lshlrev_b64 v[4:5], 17, v[2:3]
	s_lshl_b64 s[48:49], s[70:71], 1
	v_lshl_add_u64 v[4:5], s[44:45], 0, v[4:5]
	v_lshlrev_b32_e32 v2, 4, v2
	v_lshl_add_u64 v[6:7], v[174:175], 0, s[48:49]
	v_ashrrev_i32_e32 v3, 31, v2
	global_load_dwordx4 v[80:83], v[6:7], off offset:3072
	v_lshl_add_u64 v[6:7], v[176:177], 1, v[4:5]
	v_lshl_add_u64 v[2:3], v[2:3], 1, v[204:205]
	v_lshl_add_u64 v[6:7], v[6:7], 0, s[34:35]
	v_cndmask_b32_e64 v3, v7, v3, s[36:37]
	v_cndmask_b32_e64 v2, v6, v2, s[36:37]
	global_load_dwordx4 v[84:87], v[2:3], off
	v_lshl_add_u64 v[2:3], v[178:179], 0, s[48:49]
	v_lshl_add_u64 v[6:7], v[182:183], 0, s[48:49]
	global_load_dwordx4 v[88:91], v[2:3], off offset:3072
	v_lshl_add_u64 v[2:3], v[180:181], 1, v[4:5]
	global_load_dwordx4 v[96:99], v[6:7], off offset:3072
	global_load_dwordx4 v[100:103], v[2:3], off offset:96
	global_load_dwordx4 v[92:95], v[2:3], off offset:224
	v_lshl_add_u64 v[6:7], v[184:185], 0, s[48:49]
	global_load_dwordx4 v[104:107], v[6:7], off offset:3072
	v_lshl_add_u64 v[6:7], v[196:197], 0, s[48:49]
	global_load_dwordx4 v[112:115], v[6:7], off offset:3072
	global_load_dwordx4 v[116:119], v[2:3], off offset:352
	global_load_dwordx4 v[108:111], v[2:3], off offset:480
	v_lshl_add_u64 v[6:7], v[198:199], 0, s[48:49]
	global_load_dwordx4 v[120:123], v[6:7], off offset:3072
	global_load_dwordx4 v[128:131], v[2:3], off offset:608
	v_lshl_add_u64 v[2:3], v[200:201], 0, s[48:49]
	v_mov_b32_e32 v213, v1
	global_load_dwordx4 v[124:127], v[2:3], off offset:3072
	v_lshl_add_u64 v[2:3], v[4:5], 0, v[212:213]
	global_load_dwordx4 v[132:135], v[2:3], off offset:-32
	s_add_i32 s41, s53, 30
	s_ashr_i32 s58, s41, 6
	s_cmp_lt_i32 s58, s55
	v_add_u32_e32 v152, s53, v239
	s_cbranch_scc1 .LBB0_283
	s_mul_i32 s48, s58, 0x2400
	s_mul_i32 s49, s55, 0x2400
	s_lshl_b32 s41, s58, 6
	s_sub_i32 s48, s48, s49
	v_mov_b32_e32 v16, 0
	v_subrev_u32_e32 v0, s41, v152
	s_add_i32 s41, s41, 64
	v_add_u32_e32 v10, s48, v240
	v_mov_b32_e32 v211, 1.0
	v_mov_b32_e32 v17, v16
	v_mov_b32_e32 v18, v16
	v_mov_b32_e32 v19, v16
	v_mov_b32_e32 v20, v16
	v_mov_b32_e32 v21, v16
	v_mov_b32_e32 v22, v16
	v_mov_b32_e32 v23, v16
	v_mov_b32_e32 v24, v16
	v_mov_b32_e32 v25, v16
	v_mov_b32_e32 v26, v16
	v_mov_b32_e32 v27, v16
	v_mov_b32_e32 v28, v16
	v_mov_b32_e32 v29, v16
	v_mov_b32_e32 v30, v16
	v_mov_b32_e32 v31, v16
	v_mov_b32_e32 v32, v16
	v_mov_b32_e32 v33, v16
	v_mov_b32_e32 v34, v16
	v_mov_b32_e32 v35, v16
	v_mov_b32_e32 v36, v16
	v_mov_b32_e32 v37, v16
	v_mov_b32_e32 v38, v16
	v_mov_b32_e32 v39, v16
	v_mov_b32_e32 v40, v16
	v_mov_b32_e32 v41, v16
	v_mov_b32_e32 v42, v16
	v_mov_b32_e32 v43, v16
	v_mov_b32_e32 v44, v16
	v_mov_b32_e32 v45, v16
	v_mov_b32_e32 v46, v16
	v_mov_b32_e32 v47, v16
	s_branch .LBB0_281
